# replace the post-prologue cooperative-groups grid sync with an instance of the two-level xcd barrier placed after loop-invariant setup
# speedup vs baseline: 1.0093x; 1.0031x over previous
;     __host__ __device__ bool next(int i, Unit& u) const {
;         const long L = (long)i * G + c; if (L >= nwg) return false;
;         int wgid = (int)L; { const int q = nwg / NXCD, r = nwg % NXCD, xcd = wgid % NXCD, off = wgid / NXCD; wgid = (xcd < r ? xcd * (q + 1) : r * (q + 1) + (xcd - r) * q) + off; }
;         const int nig = WGM * nN, gid = wgid / nig, fm = gid * WGM, gsz = (nM - fm) < WGM ? (nM - fm) : WGM;
;         u.pm = fm + ((wgid % nig) % gsz); u.pn = (wgid % nig) / gsz; return true;
; __global__ void __launch_bounds__(NWAVES * 64, 2) hymba_fwd(Args args) {
;     ...
;     cg::this_grid().sync();
;     for (int step = 0; step < 3 * DEPTH; ++step) {
;         const int l = step / 3, kind = step % 3;
;     ...
;         if (kind != 1) {
;             const int f = kind >> 1;
;             { pg8::Gemm g{XB, (const bf16*)(wl + (f ? OFF_GU2 : OFF_GU1)), M, NGU, D}; pg8::StaticOrder S; S.init(M, NGU, G, bx);
.LBB0_68:
	s_load_dwordx2 s[4:5], s[12:13], 0x4
	s_waitcnt lgkmcnt(0)
	s_ashr_i32 s49, s2, 31
	s_cmpk_lt_i32 s2, 0x580
	s_mul_i32 s99, s5, s4
	s_cselect_b64 s[4:5], -1, 0
	s_lshr_b32 s1, s49, 29
	v_writelane_b32 v255, s4, 2
	s_add_i32 s1, s2, s1
	s_ashr_i32 s98, s3, 31
	v_writelane_b32 v255, s5, 3
	s_ashr_i32 s4, s1, 3
	s_and_b32 s1, s1, -8
	s_sub_i32 s1, s2, s1
	s_add_u32 s54, s38, 0x200
	s_addc_u32 s55, s39, 0
	s_add_u32 s56, s38, 0x1000
	s_addc_u32 s57, s39, 0
	s_add_u32 s58, s38, 0x1100
	s_addc_u32 s59, s39, 0
	s_add_u32 s60, s38, 0x1200
	s_addc_u32 s61, s39, 0
	s_add_u32 s62, s38, 0x1300
	s_addc_u32 s63, s39, 0
	s_add_u32 s6, s38, 0x3400
	s_addc_u32 s7, s39, 0
	s_add_u32 s66, s38, 0x3500
	s_addc_u32 s67, s39, 0
	v_writelane_b32 v255, s6, 4
	s_cmpk_lt_i32 s2, 0x100
	s_movk_i32 s74, 0xb1
	v_writelane_b32 v255, s7, 5
	s_cselect_b64 s[6:7], -1, 0
	s_lshl_b32 s5, s1, 5
	s_cmpk_lt_i32 s2, 0x200
	s_cselect_b64 s[70:71], -1, 0
	s_ashr_i32 s8, s3, 3
	v_writelane_b32 v255, s6, 6
	s_mul_i32 s8, s8, s1
	s_add_i32 s8, s8, s4
	v_writelane_b32 v255, s7, 7
	s_lshl_b32 s6, s1, 6
	s_and_b32 s7, s3, 7
	s_cmpk_lg_i32 s3, 0x100
	s_cselect_b64 s[72:73], -1, 0
	s_lshl_b32 s9, s2, 8
	s_and_b32 s9, s9, 0x700
	s_and_b32 s10, s2, -8
	s_add_i32 s9, s9, s10
	s_add_i32 s9, s9, s0
	s_cmpk_eq_i32 s3, 0x100
	s_cselect_b32 s14, s9, s48
	s_cmpk_lt_i32 s14, 0x800
	s_cselect_b64 s[10:11], -1, 0
	v_writelane_b32 v255, s10, 8
	s_cmp_lt_i32 s1, 0
	s_mul_i32 s0, s1, 33
	v_writelane_b32 v255, s11, 9
	s_cselect_b32 s10, s74, 0xb0
	s_mul_i32 s9, s1, 0x41
	s_mul_i32 s1, s1, s10
	s_cselect_b32 s5, s0, s5
	s_cselect_b32 s6, s9, s6
	s_add_i32 s1, s1, s4
	s_mul_hi_i32 s0, s1, 0x2e8ba2e9
	s_lshr_b32 s9, s0, 31
	s_ashr_i32 s0, s0, 5
	s_add_i32 s0, s0, s9
	s_mul_i32 s9, s0, 0xb0
	s_lshl_b32 s10, s0, 3
	s_sub_i32 s0, 64, s10
	s_sub_i32 s9, s1, s9
	s_min_i32 s11, s0, 8
	s_bfe_u32 s0, s9, 0x3001c
	s_add_i32 s1, s9, s0
	s_sext_i32_i16 s12, s1
	s_and_b32 s1, s1, 0xfff8
	s_sub_i32 s1, s9, s1
	s_sext_i32_i16 s1, s1
	s_add_i32 s16, s10, s1
	s_ashr_i32 s1, s12, 3
	s_lshr_b32 s0, s12, 3
	v_writelane_b32 v255, s1, 10
	s_mov_b32 s12, s16
	s_ashr_i32 s17, s16, 31
	v_writelane_b32 v255, s12, 11
	s_bfe_i64 s[0:1], s[0:1], 0x100000
	s_lshl_b64 s[0:1], s[0:1], 19
	v_writelane_b32 v255, s13, 12
	s_lshl_b64 s[12:13], s[16:17], 19
	v_writelane_b32 v255, s12, 13
	s_barrier
	s_nop 0
	v_writelane_b32 v255, s13, 14
	v_writelane_b32 v255, s0, 15
	s_load_dwordx2 s[18:19], s[64:65], 0x58
	s_mov_b32 s77, 0
	v_writelane_b32 v255, s1, 16
	s_add_i32 s0, s5, s4
	s_ashr_i32 s1, s0, 31
	s_lshr_b32 s1, s1, 27
	s_add_i32 s1, s0, s1
	s_ashr_i32 s5, s1, 5
	s_and_b32 s1, s1, 0xffe0
	s_sub_i32 s1, s0, s1
	s_bfe_i32 s0, s1, 0x80000
	s_bfe_u32 s0, s0, 0x3000c
	s_add_i32 s12, s1, s0
	s_bfe_i32 s0, s12, 0x80000
	s_and_b32 s12, s12, 0xf8
	s_sub_i32 s1, s1, s12
	s_lshl_b32 s5, s5, 3
	s_sext_i32_i8 s1, s1
	s_add_i32 s84, s5, s1
	s_add_i32 s1, s6, s4
	s_ashr_i32 s4, s1, 31
	s_lshr_b32 s4, s4, 26
	s_add_i32 s4, s1, s4
	s_sext_i32_i16 s13, s0
	s_ashr_i32 s5, s4, 6
	s_andn2_b32 s4, s4, 63
	s_lshr_b32 s0, s13, 3
	s_ashr_i32 s75, s13, 3
	s_sub_i32 s13, s1, s4
	s_bfe_i32 s1, s13, 0x80000
	s_bfe_u32 s1, s1, 0x3000c
	s_add_i32 s1, s13, s1
	s_lshl_b32 s6, s5, 3
	s_bfe_i32 s4, s1, 0x80000
	s_and_b32 s1, s1, 0xf8
	s_sub_i32 s5, 64, s6
	s_sub_i32 s1, s13, s1
	s_min_i32 s12, s5, 8
	s_sext_i32_i16 s5, s4
	s_sext_i32_i8 s1, s1
	s_lshr_b32 s4, s5, 3
	s_add_i32 s16, s6, s1
	s_ashr_i32 s1, s5, 3
	s_cmp_eq_u32 s7, 0
	v_writelane_b32 v255, s1, 17
	s_cselect_b32 s1, s8, s2
	s_abs_i32 s7, s11
	v_cvt_f32_u32_e32 v0, s7
	s_waitcnt lgkmcnt(0)
	v_writelane_b32 v255, s18, 18
	s_mov_b32 s8, s16
	s_ashr_i32 s17, s16, 31
	v_rcp_iflag_f32_e32 v0, v0
	v_writelane_b32 v255, s19, 19
	v_writelane_b32 v255, s8, 20
	s_lshl_b64 s[16:17], s[16:17], 19
	s_bfe_i64 s[4:5], s[4:5], 0x100000
	v_writelane_b32 v255, s9, 21
	v_writelane_b32 v255, s16, 22
	v_mul_f32_e32 v0, 0x4f7ffffe, v0
	s_lshl_b64 s[4:5], s[4:5], 19
	v_writelane_b32 v255, s17, 23
	v_cvt_u32_f32_e32 v0, v0
	s_ashr_i32 s85, s84, 31
	v_writelane_b32 v255, s4, 24
	s_and_b32 s80, s1, 31
	s_ashr_i32 s81, s1, 5
	v_writelane_b32 v255, s5, 25
	s_lshl_b64 s[4:5], s[84:85], 19
	v_writelane_b32 v255, s4, 26
	s_bfe_i64 s[0:1], s[0:1], 0x100000
	s_lshl_b64 s[0:1], s[0:1], 19
	v_writelane_b32 v255, s5, 27
	s_sub_i32 s4, 0, s7
	v_readfirstlane_b32 s5, v0
	s_mul_i32 s4, s4, s5
	v_writelane_b32 v255, s0, 28
	s_mul_hi_u32 s4, s5, s4
	s_add_i32 s5, s5, s4
	v_writelane_b32 v255, s1, 29
	s_abs_i32 s1, s9
	s_mul_hi_u32 s4, s1, s5
	s_mul_i32 s4, s4, s7
	s_sub_i32 s1, s1, s4
	s_xor_b32 s82, s80, 63
	s_ashr_i32 s0, s9, 31
	s_sub_i32 s4, s1, s7
	s_cmp_ge_u32 s1, s7
	s_cselect_b32 s1, s4, s1
	s_sub_i32 s4, s1, s7
	s_cmp_ge_u32 s1, s7
	s_cselect_b32 s1, s4, s1
	s_abs_i32 s4, s12
	v_cvt_f32_u32_e32 v0, s4
	s_sub_i32 s5, 0, s4
	s_xor_b32 s1, s1, s0
	s_sub_i32 s0, s1, s0
	v_rcp_iflag_f32_e32 v0, v0
	s_abs_i32 s1, s13
	s_add_i32 s0, s10, s0
	v_writelane_b32 v255, s0, 30
	v_mul_f32_e32 v0, 0x4f7ffffe, v0
	v_cvt_u32_f32_e32 v0, v0
	s_ashr_i32 s0, s13, 31
	s_mul_i32 s99, s99, s3
	v_mov_b32_e32 v225, 0x358637bd
	v_readfirstlane_b32 s7, v0
	s_mul_i32 s5, s5, s7
	s_mul_hi_u32 s5, s7, s5
	s_add_i32 s7, s7, s5
	s_mul_hi_u32 s5, s1, s7
	s_mul_i32 s5, s5, s4
	s_sub_i32 s1, s1, s5
	s_sub_i32 s5, s1, s4
	s_cmp_ge_u32 s1, s4
	s_cselect_b32 s1, s5, s1
	s_sub_i32 s5, s1, s4
	s_cmp_ge_u32 s1, s4
	s_cselect_b32 s1, s5, s1
	s_xor_b32 s1, s1, s0
	s_sub_i32 s0, s1, s0
	s_add_i32 s0, s6, s0
	v_writelane_b32 v255, s0, 31
	v_writelane_b32 v255, s14, 32
	s_lshl_b32 s0, s14, 3
	v_writelane_b32 v255, s0, 33
	v_writelane_b32 v255, s64, 34
	s_load_dwordx8 s[4:11], s[64:65], 0x38
	s_lshl_b32 s85, s3, 6
	v_writelane_b32 v255, s65, 35
	v_mov_b32_e32 v161, 0
	s_mov_b32 s90, 1.0
	s_waitcnt lgkmcnt(0)
	v_writelane_b32 v255, s4, 36
	s_movk_i32 s91, 0x1600
	s_add_i32 s92, 0, 0x23fc0
	v_writelane_b32 v255, s5, 37
	v_writelane_b32 v255, s6, 38
	v_writelane_b32 v255, s7, 39
	v_writelane_b32 v255, s8, 40
	v_writelane_b32 v255, s9, 41
	v_writelane_b32 v255, s10, 42
	s_add_i32 s93, 0, 0x23fc4
	v_mov_b32_e32 v254, 1
	s_mov_b32 s94, 0xffff0000
	s_movk_i32 s95, 0x1080
	s_mov_b32 s96, 0x6c00000
	s_movk_i32 s97, 0x7fff
	v_mov_b32_e32 v229, 0xff800000
	v_mbcnt_hi_u32_b32 v228, -1, v1
	s_mov_b32 s83, 0
	s_mov_b64 s[50:51], 0x80
	s_mov_b64 s[88:89], 0x42000
	s_mov_b64 s[78:79], 0x84000
	v_writelane_b32 v255, s11, 43

; __device__ __forceinline__ void xcd_barrier(const XcdBarrier& b) {
;     ...
;             __builtin_amdgcn_fence(__ATOMIC_ACQUIRE, "agent");
;             asm volatile("s_waitcnt vmcnt(0)" ::: "memory");
;         }
;     }
;     __syncthreads();
.Lxbp_done:
	s_or_b64 exec, exec, s[4:5]
	s_waitcnt lgkmcnt(0)
	s_barrier
	s_branch .LBB0_82
.LBB0_79:
	s_or_b64 exec, exec, s[10:11]
	s_waitcnt vmcnt(0)
